# v22 with one lgkmcnt(0) before the PV MFMAs instead of counted waits between them
# baseline (speedup 1.0000x reference)
.Lstg_b1:
	s_waitcnt lgkmcnt(0)
	v_mfma_scale_f32_32x32x64_f8f6f4 v[64:79], v[2:9], v[194:201], v[64:79], v240, v240 op_sel_hi:[0,0,0]
	v_exp_f32_e32 v144, v160
	v_exp_f32_e32 v145, v161
	v_exp_f32_e32 v146, v162
	v_mfma_scale_f32_32x32x64_f8f6f4 v[48:63], v[2:9], v[148:155], v[48:63], v240, v240 op_sel_hi:[0,0,0]
	v_exp_f32_e32 v147, v163
	v_exp_f32_e32 v148, v164
	v_exp_f32_e32 v149, v165
	v_mfma_scale_f32_32x32x64_f8f6f4 v[32:47], v[2:9], v[120:127], v[32:47], v240, v240 op_sel_hi:[0,0,0]
	v_exp_f32_e32 v150, v166
	v_exp_f32_e32 v151, v167
	v_exp_f32_e32 v152, v168
	v_mfma_scale_f32_32x32x64_f8f6f4 v[16:31], v[2:9], v[112:119], v[16:31], v240, v240 op_sel_hi:[0,0,0]
	v_exp_f32_e32 v153, v169
	v_exp_f32_e32 v154, v170
	v_exp_f32_e32 v155, v171
	v_mfma_scale_f32_32x32x64_f8f6f4 v[80:95], v[2:9], v[228:235], v[80:95], v240, v240 op_sel_hi:[0,0,0]
	v_exp_f32_e32 v156, v172
	v_exp_f32_e32 v157, v173
	v_exp_f32_e32 v158, v174
	v_exp_f32_e32 v159, v175
	s_waitcnt vmcnt(2)
	s_cmp_eq_u32 s93, 0
	s_cbranch_scc1 .LBB0_379
	s_mov_b32 s93, 0
	s_and_saveexec_b64 s[56:57], s[4:5]
	ds_write_b32 v236, v1 offset:128
	s_or_b64 exec, exec, s[56:57]
	s_waitcnt lgkmcnt(0)
	v_add_u32_e32 v1, s67, v237
	ds_read_b128 v[2:5], v1 offset:224
	ds_read_b128 v[6:9], v1 offset:192
	ds_read_b128 v[10:13], v1 offset:160
	ds_read_b128 v[112:115], v1 offset:128
	s_waitcnt lgkmcnt(0)
	v_pk_mul_f32 v[76:77], v[76:77], v[2:3]
	v_pk_mul_f32 v[72:73], v[72:73], v[6:7]
	v_pk_mul_f32 v[68:69], v[68:69], v[10:11]
	v_pk_mul_f32 v[78:79], v[78:79], v[4:5]
	v_pk_mul_f32 v[74:75], v[74:75], v[8:9]
	v_pk_mul_f32 v[70:71], v[70:71], v[12:13]
	v_pk_mul_f32 v[66:67], v[66:67], v[114:115]
	v_pk_mul_f32 v[64:65], v[64:65], v[112:113]
	v_pk_mul_f32 v[60:61], v[60:61], v[2:3]
	v_pk_mul_f32 v[56:57], v[56:57], v[6:7]
	v_pk_mul_f32 v[52:53], v[52:53], v[10:11]
	v_pk_mul_f32 v[62:63], v[62:63], v[4:5]
	v_pk_mul_f32 v[58:59], v[58:59], v[8:9]
	v_pk_mul_f32 v[54:55], v[54:55], v[12:13]
	v_pk_mul_f32 v[50:51], v[50:51], v[114:115]
	v_pk_mul_f32 v[48:49], v[48:49], v[112:113]
	v_pk_mul_f32 v[44:45], v[44:45], v[2:3]
	v_pk_mul_f32 v[40:41], v[40:41], v[6:7]
	v_pk_mul_f32 v[36:37], v[36:37], v[10:11]
	v_pk_mul_f32 v[46:47], v[46:47], v[4:5]
	v_pk_mul_f32 v[42:43], v[42:43], v[8:9]
	v_pk_mul_f32 v[38:39], v[38:39], v[12:13]
	v_pk_mul_f32 v[34:35], v[34:35], v[114:115]
	v_pk_mul_f32 v[32:33], v[32:33], v[112:113]
	v_pk_mul_f32 v[28:29], v[28:29], v[2:3]
	v_pk_mul_f32 v[24:25], v[24:25], v[6:7]
	v_pk_mul_f32 v[20:21], v[20:21], v[10:11]
	v_pk_mul_f32 v[30:31], v[30:31], v[4:5]
	v_pk_mul_f32 v[26:27], v[26:27], v[8:9]
	v_pk_mul_f32 v[22:23], v[22:23], v[12:13]
	v_pk_mul_f32 v[18:19], v[18:19], v[114:115]
	v_pk_mul_f32 v[16:17], v[16:17], v[112:113]
	v_pk_mul_f32 v[92:93], v[92:93], v[2:3]
	v_pk_mul_f32 v[88:89], v[88:89], v[6:7]
	v_pk_mul_f32 v[84:85], v[84:85], v[10:11]
	v_pk_mul_f32 v[94:95], v[94:95], v[4:5]
	v_pk_mul_f32 v[90:91], v[90:91], v[8:9]
	v_pk_mul_f32 v[86:87], v[86:87], v[12:13]
	v_pk_mul_f32 v[82:83], v[82:83], v[114:115]
	v_pk_mul_f32 v[80:81], v[80:81], v[112:113]

.Lstg_b2:
	s_waitcnt lgkmcnt(0)
	v_mfma_scale_f32_32x32x64_f8f6f4 v[64:79], v[2:9], v[194:201], v[64:79], v240, v240 op_sel_hi:[0,0,0]
	v_exp_f32_e32 v144, v160
	v_exp_f32_e32 v145, v161
	v_exp_f32_e32 v146, v162
	v_mfma_scale_f32_32x32x64_f8f6f4 v[48:63], v[2:9], v[148:155], v[48:63], v240, v240 op_sel_hi:[0,0,0]
	v_exp_f32_e32 v147, v163
	v_exp_f32_e32 v148, v164
	v_exp_f32_e32 v149, v165
	v_mfma_scale_f32_32x32x64_f8f6f4 v[32:47], v[2:9], v[136:143], v[32:47], v240, v240 op_sel_hi:[0,0,0]
	v_exp_f32_e32 v150, v166
	v_exp_f32_e32 v151, v167
	v_exp_f32_e32 v152, v168
	v_mfma_scale_f32_32x32x64_f8f6f4 v[16:31], v[2:9], v[128:135], v[16:31], v240, v240 op_sel_hi:[0,0,0]
	v_exp_f32_e32 v153, v169
	v_exp_f32_e32 v154, v170
	v_exp_f32_e32 v155, v171
	v_mfma_scale_f32_32x32x64_f8f6f4 v[80:95], v[2:9], v[228:235], v[80:95], v240, v240 op_sel_hi:[0,0,0]
	v_exp_f32_e32 v156, v172
	v_exp_f32_e32 v157, v173
	v_exp_f32_e32 v158, v174
	v_exp_f32_e32 v159, v175
	s_waitcnt vmcnt(2)
	s_cmp_eq_u32 s93, 0
	s_cbranch_scc1 .LBB0_373
	s_mov_b32 s93, 0
	s_and_saveexec_b64 s[56:57], s[4:5]
	s_cbranch_execz .LBB0_372
	ds_write_b32 v236, v1 offset:128
	s_branch .LBB0_372
